# P6: row sum-of-squares partials of the workgroup's panel staged once in spare LDS; unit epilogues read them with ds_read_b128 instead of global loads
# speedup vs baseline: 1.0041x; 1.0028x over previous
; DI int tid_of(int wave0) { int t = wave0 * 64 + lane_id(); asm volatile("" : "+v"(t)); return t; }
; #define PG8_BAR __builtin_amdgcn_s_barrier()
;     __device__ __forceinline__ void operator()(const f32x4 (&acc)[2][2][4][2], const Unit& u, int wr, int wc, int fr, int fq) const {
;         float rsv[8];
; #pragma unroll
;         for (int idx = 0; idx < 8; ++idx) { const f32x4 q = *(const f32x4*)(rowss + (size_t)(u.pm * BM + (idx >> 2) * HALF + wr * 64 + (idx & 3) * 16 + fr) * 4); rsv[idx] = (q[0] + q[1]) + (q[2] + q[3]); }
;     const int tid = tid_of(wave0), wid = wave0, lane = tid & 63, wr = wid >> 2, wc = wid & 3, fr = lane & 15, fq = lane >> 4;
;     const int K = g.K;
;     unsigned voffA[2], voffB[2];
; #pragma unroll
;     for (int i = 0; i < 2; ++i) { int R, C; stage_rc(tid * 16 + i * 8192, R, C); const int Rb = (R >> 5) * 64 + (Epi::PERM ? perm32(R & 31) : (R & 31));
;         voffA[i] = (unsigned)(R * K + C) * 2u; voffB[i] = (unsigned)(Rb * K + C) * 2u; }
;     const size_t kstep = (size_t)(BK * 2);
;     const size_t hstep = (size_t)HALF * K * 2;
;     const size_t tstep = 2 * hstep;
;     const size_t hstepB = (size_t)32 * K * 2;
;     const unsigned ldsw = (unsigned)wid * 1024u;
;     const int aoff = lds_byte(wr * 64 + fr, fq * 8), boff = lds_byte(wc * 32 + fr, fq * 8);
;     ...
;     Unit cur, nxt; int ui = 0;
;     if (!S.next(0, cur)) return;
;     f32x4 acc[2][2][4][2];
; #pragma unroll
;     for (int a = 0; a < 2; ++a)
; #pragma unroll
;         for (int b = 0; b < 2; ++b)
; #pragma unroll
;             for (int m = 0; m < 4; ++m)
; #pragma unroll
;                 for (int n = 0; n < 2; ++n) acc[a][b][m][n] = (f32x4){0.f, 0.f, 0.f, 0.f};
;     bf16x8 At[4][2], B0[2][2], B1[2][2];
;     const char* cA = (const char*)g.A + (size_t)cur.pm * tstep + (size_t)cur.k0 * (BK * 2); const char* cB = (const char*)g.Bt + (size_t)cur.pn * tstep + (size_t)cur.k0 * (BK * 2);
;     S.a_ready(cur);
;     if constexpr (SP2) {
;         PG8_STAGE(PG8_SB(0, 0), cB, voffB); PG8_STAGE(PG8_SB(0, 1), cB + hstepB, voffB); PG8_STAGEA(PG8_SA(0, 0), cA, voffA); PG8_STAGEA(PG8_SA(0, 1), cA + hstep, voffA);
;         if (wr == 1) PG8_BAR;
;         PG8_WAIT_V(2); PG8_BAR;
;         PG8_STAGE(PG8_SB(1, 0), cB + kstep, voffB); PG8_STAGEA(PG8_SA(1, 0), cA + kstep, voffA); PG8_STAGE(PG8_SB(1, 1), cB + hstepB + kstep, voffB);
;         PG8_WAIT_V(6); PG8_BAR;
.LBB0_968:
	s_or_b64 exec, exec, s[0:1]
	s_lshl_b32 s12, s49, 4
	s_add_u32 s4, s68, 0x3200000
	s_addc_u32 s5, s69, 0
	v_mov_b32_e32 v10, v175
	s_cmp_ge_i32 s2, s12
	s_waitcnt lgkmcnt(0)
	s_barrier
	s_cbranch_scc1 .LBB0_984
	v_lshlrev_b32_e32 v0, 4, v10
	v_add_u32_e32 v1, 0x2000, v0
	v_ashrrev_i32_e32 v2, 31, v1
	v_lshrrev_b32_e32 v2, 22, v2
	v_add_u32_e32 v2, v1, v2
	v_ashrrev_i32_e32 v8, 10, v2
	v_mul_i32_i24_e32 v2, 0x400, v8
	v_sub_u32_e32 v1, v1, v2
	v_lshrrev_b32_e32 v2, 4, v1
	v_bitop3_b32 v1, v2, v1, 32 bitop3:0x6c
	v_ashrrev_i32_e32 v2, 31, v1
	v_lshrrev_b32_e32 v2, 26, v2
	v_add_u32_e32 v2, v1, v2
	v_lshlrev_b32_e32 v4, 3, v8
	v_ashrrev_i32_e32 v9, 6, v2
	v_and_b32_e32 v4, -16, v4
	v_add_u32_e32 v4, v9, v4
	v_lshrrev_b32_e32 v5, 2, v4
	v_lshlrev_b32_e32 v6, 1, v4
	v_and_b32_e32 v2, 0xc0, v2
	v_and_b32_e32 v3, 3, v9
	v_and_b32_e32 v5, 4, v5
	v_and_b32_e32 v6, 0x1fffd8, v6
	v_sub_u32_e32 v1, v1, v2
	v_mov_b32_e32 v2, 1
	v_or3_b32 v3, v3, v5, v6
	v_lshlrev_b32_e32 v5, 5, v8
	v_ashrrev_i16_sdwa v1, v2, sext(v1) dst_sel:DWORD dst_unused:UNUSED_PAD src0_sel:DWORD src1_sel:BYTE_0
	s_add_u32 s3, s68, 0xa00000
	v_and_b32_e32 v5, 32, v5
	v_bfe_i32 v11, v1, 0, 16
	s_addc_u32 s21, s69, 0
	v_add_lshl_u32 v1, v5, v11, 1
	s_ashr_i32 s44, s2, 31
	v_lshl_add_u32 v128, v3, 11, v1
	v_lshl_add_u32 v130, v4, 11, v1
	v_bfe_i32 v1, v10, 27, 1
	s_lshr_b32 s0, s44, 29
	v_lshrrev_b32_e32 v1, 22, v1
	s_add_i32 s0, s2, s0
	v_add_u32_e32 v1, v0, v1
	s_lshl_b32 s23, s49, 1
	s_ashr_i32 s1, s0, 3
	s_and_b32 s0, s0, -8
	v_and_b32_e32 v1, 0xfffffc00, v1
	s_sub_i32 s0, s2, s0
	s_or_b32 s45, s23, 1
	v_sub_u32_e32 v0, v0, v1
	v_ashrrev_i32_e32 v3, 31, v10
	s_cmp_lt_i32 s0, 0
	v_lshrrev_b32_e32 v1, 4, v0
	v_lshrrev_b32_e32 v3, 26, v3
	s_cselect_b32 s13, s45, s23
	v_bitop3_b32 v1, v1, v0, 32 bitop3:0x6c
	v_ashrrev_i32_e32 v0, 31, v0
	v_add_u32_e32 v3, v10, v3
	s_mul_i32 s0, s13, s0
	v_lshrrev_b32_e32 v0, 26, v0
	v_ashrrev_i32_e32 v13, 6, v3
	s_add_i32 s0, s0, s1
	v_add_u32_e32 v0, v1, v0
	v_lshlrev_b32_e32 v3, 3, v13
	s_ashr_i32 s1, s0, 31
	v_ashrrev_i32_e32 v12, 6, v0
	v_and_b32_e32 v3, -16, v3
	s_lshr_b32 s1, s1, 25
	v_add_u32_e32 v3, v12, v3
	s_add_i32 s1, s0, s1
	v_lshrrev_b32_e32 v4, 2, v3
	v_lshlrev_b32_e32 v5, 1, v3
	s_ashr_i32 s13, s1, 7
	v_and_b32_e32 v0, 3, v12
	v_and_b32_e32 v4, 4, v4
	v_and_b32_e32 v5, 0x1fffd8, v5
	s_lshl_b32 s13, s13, 3
	v_or3_b32 v0, v0, v4, v5
	v_mul_i32_i24_e32 v5, 64, v12
	s_sub_i32 s14, s49, s13
	v_sub_u32_e32 v1, v1, v5
	s_min_i32 s14, s14, 8
	v_ashrrev_i16_sdwa v1, v2, sext(v1) dst_sel:DWORD dst_unused:UNUSED_PAD src0_sel:DWORD src1_sel:BYTE_0
	s_abs_i32 s15, s14
	v_bfe_i32 v14, v1, 0, 16
	v_cvt_f32_u32_e32 v1, s15
	v_lshlrev_b32_e32 v4, 5, v13
	v_and_b32_e32 v4, 32, v4
	v_add_lshl_u32 v2, v4, v14, 1
	v_lshl_add_u32 v132, v0, 11, v2
	v_rcp_iflag_f32_e32 v0, v1
	s_sub_i32 s17, 0, s15
	s_and_b32 s1, s1, 0xffffff80
	s_sub_i32 s0, s0, s1
	v_mul_f32_e32 v0, 0x4f7ffffe, v0
	v_cvt_u32_f32_e32 v0, v0
	s_abs_i32 s16, s0
	s_xor_b32 s1, s0, s14
	s_ashr_i32 s1, s1, 31
	v_readfirstlane_b32 s18, v0
	s_mul_i32 s17, s17, s18
	s_mul_hi_u32 s17, s18, s17
	s_add_i32 s18, s18, s17
	s_mul_hi_u32 s17, s16, s18
	s_mul_i32 s18, s17, s15
	s_sub_i32 s16, s16, s18
	s_add_i32 s18, s17, 1
	s_sub_i32 s19, s16, s15
	s_cmp_ge_u32 s16, s15
	s_cselect_b32 s17, s18, s17
	s_cselect_b32 s16, s19, s16
	s_add_i32 s18, s17, 1
	s_cmp_ge_u32 s16, s15
	s_cselect_b32 s15, s18, s17
	s_xor_b32 s15, s15, s1
	s_sub_i32 s34, s15, s1
	s_mul_i32 s1, s34, s14
	s_sub_i32 s0, s0, s1
	s_add_i32 s36, s13, s0
	v_lshlrev_b32_e32 v251, 4, v175
	s_lshl_b32 s98, s36, 12
	s_add_u32 s98, s98, 0x120000
	v_add_u32_e32 v250, s98, v251
	v_add_u32_e32 v251, 0x21000, v251
	global_load_dwordx4 v[246:249], v250, s[68:69]
	s_ashr_i32 s37, s36, 31
	s_ashr_i32 s35, s34, 31
	s_lshl_b64 s[0:1], s[36:37], 19
	s_lshl_b64 s[14:15], s[34:35], 19
	s_add_u32 s40, s3, s14
	s_addc_u32 s41, s21, s15
	s_add_i32 s37, s67, 0
	s_add_i32 m0, s37, 0x10000
	v_lshl_add_u32 v134, v3, 11, v2
	global_load_lds_dwordx4 v132, s[40:41]
	s_add_i32 m0, s37, 0x12000
	s_add_u32 s14, s40, 0x10000
	global_load_lds_dwordx4 v128, s[40:41]
	s_addc_u32 s15, s41, 0
	s_add_i32 m0, s37, 0x14000
	v_mov_b32_e32 v137, 0
	global_load_lds_dwordx4 v132, s[14:15]
	s_add_i32 m0, s37, 0x16000
	s_add_u32 s38, s8, s0
	s_addc_u32 s39, s9, s1
	s_add_i32 s46, s37, 0x2000
	global_load_lds_dwordx4 v128, s[14:15]
	s_mov_b32 m0, s37
	s_add_u32 s0, s38, 0x40000
	global_load_lds_dwordx4 v134, s[38:39]
	s_mov_b32 m0, s46
	s_addc_u32 s1, s39, 0
	s_add_i32 s47, s37, 0x4000
	global_load_lds_dwordx4 v130, s[38:39]
	s_mov_b32 m0, s47
	s_add_i32 s50, s37, 0x6000
	global_load_lds_dwordx4 v134, s[0:1]
	s_mov_b32 m0, s50
	v_mov_b32_e32 v133, v137
	global_load_lds_dwordx4 v130, s[0:1]
	v_readlane_b32 s0, v255, 17
	v_mov_b32_e32 v129, v137
	v_mov_b32_e32 v135, v137
	v_mov_b32_e32 v131, v137
	s_cmp_eq_u32 s0, 1
	s_mov_b32 s13, 0
	v_lshl_add_u64 v[4:5], s[40:41], 0, v[132:133]
	v_lshl_add_u64 v[2:3], s[40:41], 0, v[128:129]
	v_lshl_add_u64 v[0:1], s[38:39], 0, v[134:135]
	s_cselect_b64 s[14:15], -1, 0
	s_cmp_lg_u32 s0, 1
	v_lshl_add_u64 v[6:7], s[38:39], 0, v[130:131]
	s_cbranch_scc1 .LBB0_971
	s_barrier
; #define PG8_STAGE(bufoff, gbase, voff) do { _Pragma("unroll") for (int _i = 0; _i < 2; ++_i) \
;         __builtin_amdgcn_global_load_lds((const unsigned*)((const char*)(gbase) + (voff)[_i]), (PG8_LAS unsigned*)(lds + (bufoff) + ldsw + _i * 8192), 16, 0, 0); } while (0)
; #define PG8_STAGEA(bufoff, gbase, voff) do { _Pragma("unroll") for (int _i = 0; _i < 2; ++_i) \
;         __builtin_amdgcn_global_load_lds((const unsigned*)((const char*)(gbase) + (voff)[_i]), (PG8_LAS unsigned*)(lds + (bufoff) + ldsw + _i * 8192), 16, 0, AUXA); } while (0)
; #define PG8_WAIT_V(n) asm volatile("s_waitcnt vmcnt(" #n ")" ::: "memory")
; #define PG8_BAR __builtin_amdgcn_s_barrier()
;     __device__ __forceinline__ void operator()(const f32x4 (&acc)[2][2][4][2], const Unit& u, int wr, int wc, int fr, int fq) const {
;         float rsv[8];
; #pragma unroll
;         for (int idx = 0; idx < 8; ++idx) { const f32x4 q = *(const f32x4*)(rowss + (size_t)(u.pm * BM + (idx >> 2) * HALF + wr * 64 + (idx & 3) * 16 + fr) * 4); rsv[idx] = (q[0] + q[1]) + (q[2] + q[3]); }
;     ...
;         PG8_STAGE(PG8_SB(1, 0), cB + kstep, voffB); PG8_STAGEA(PG8_SA(1, 0), cA + kstep, voffA); PG8_STAGE(PG8_SB(1, 1), cB + hstepB + kstep, voffB);
;         PG8_WAIT_V(6); PG8_BAR;
.LBB0_971:
	s_mov_b64 s[16:17], 0x80
	s_add_i32 m0, s37, 0x18000
	v_lshl_add_u64 v[4:5], v[4:5], 0, s[16:17]
	s_waitcnt vmcnt(2)
	s_barrier
	global_load_lds_dwordx4 v[4:5], off
	v_lshl_add_u64 v[2:3], v[2:3], 0, s[16:17]
	s_add_i32 m0, s37, 0x1a000
	s_add_i32 s51, s37, 0x8000
	s_add_i32 s52, s37, 0xa000
	global_load_lds_dwordx4 v[2:3], off
	v_lshl_add_u64 v[0:1], v[0:1], 0, s[16:17]
	s_mov_b32 m0, s51
	s_add_u32 s0, s40, 0x10080
	global_load_lds_dwordx4 v[0:1], off
	v_lshl_add_u64 v[0:1], v[6:7], 0, s[16:17]
	s_mov_b32 m0, s52
	s_addc_u32 s1, s41, 0
	global_load_lds_dwordx4 v[0:1], off
	s_add_i32 m0, s37, 0x1c000
	v_lshl_add_u64 v[0:1], s[0:1], 0, v[132:133]
	global_load_lds_dwordx4 v[0:1], off
	v_lshl_add_u64 v[0:1], s[0:1], 0, v[128:129]
	s_add_i32 m0, s37, 0x1e000
	s_movk_i32 s0, 0x3c0
	global_load_lds_dwordx4 v[0:1], off
	v_and_b32_e32 v1, 15, v10
	v_lshrrev_b32_e32 v0, 1, v10
	v_or_b32_e32 v168, s72, v1
	v_lshlrev_b32_e32 v200, 4, v168
	v_add_u32_e32 v200, 0x21000, v200
	v_and_b32_e32 v0, 24, v0
	v_lshlrev_b32_e32 v2, 6, v168
	v_lshlrev_b32_e32 v3, 1, v0
	v_lshlrev_b32_e32 v4, 2, v168
	v_and_or_b32 v2, v2, s0, v3
	v_and_b32_e32 v4, 32, v4
	v_readlane_b32 s0, v255, 18
	v_lshl_or_b32 v1, v1, 6, v3
	v_lshlrev_b32_e32 v3, 2, v10
	v_bitop3_b32 v2, v2, s0, v4 bitop3:0xde
	v_and_b32_e32 v3, 32, v3
	v_readlane_b32 s0, v255, 19
	s_waitcnt vmcnt(6)
	ds_write_b128 v251, v[246:249]
	v_mov_b32_e32 v139, v137
	v_mov_b32_e32 v141, v137
	v_bitop3_b32 v169, v1, s0, v3 bitop3:0xde
	v_lshlrev_b32_e32 v1, 14, v13
	v_and_b32_e32 v1, 0xffff8000, v1
	v_lshl_add_u32 v1, v12, 11, v1
	v_and_b32_e32 v3, 1, v13
	v_lshl_or_b32 v1, v3, 6, v1
	v_lshl_add_u32 v138, v14, 1, v1
	v_lshlrev_b32_e32 v1, 14, v8
	v_readlane_b32 s0, v255, 10
	v_and_b32_e32 v1, 0xffff8000, v1
	s_cmpk_lt_u32 s0, 0x100
	v_lshl_add_u32 v1, v9, 11, v1
	v_and_b32_e32 v3, 1, v8
	s_cselect_b64 s[18:19], -1, 0
	s_lshl_b32 s0, s48, 6
	v_lshl_or_b32 v1, v3, 6, v1
	s_add_i32 s54, 0, 0x10000
	s_add_i32 s55, 0, 0x14000
	s_ashr_i32 s53, s96, 31
	v_lshl_add_u32 v140, v11, 1, v1
	v_mov_b64_e32 v[142:143], s[12:13]
	v_add_u32_e32 v170, s54, v169
	v_add_u32_e32 v171, s55, v169
	v_add_u32_e32 v172, 0, v2
	s_lshl_b32 s12, s0, 1
	v_lshlrev_b32_e32 v136, 1, v0
	s_mov_b32 s20, 0x3a800000
	s_mov_b32 s22, 0x358637bd
	s_mov_b32 s56, 0x800000
	s_mov_b32 s57, s13
	s_barrier
	s_mov_b32 s99, 0
	s_branch .LBB0_974

;     __device__ __forceinline__ void operator()(const f32x4 (&acc)[2][2][4][2], const Unit& u, int wr, int wc, int fr, int fq) const {
;         float rsv[8];
; #pragma unroll
;         for (int idx = 0; idx < 8; ++idx) { const f32x4 q = *(const f32x4*)(rowss + (size_t)(u.pm * BM + (idx >> 2) * HALF + wr * 64 + (idx & 3) * 16 + fr) * 4); rsv[idx] = (q[0] + q[1]) + (q[2] + q[3]); }
.LBB0_980:
	s_cmp_lg_u32 s100, 0
	s_cbranch_scc1 .Lrsl6_slow
	v_lshl_add_u32 v202, s36, 8, v168
	v_ashrrev_i32_e32 v203, 31, v202
	v_or_b32_e32 v166, 16, v202
	v_lshl_add_u64 v[144:145], v[202:203], 4, s[10:11]
	v_ashrrev_i32_e32 v167, 31, v166
	v_or_b32_e32 v164, 32, v202
	v_lshl_add_u64 v[146:147], v[166:167], 4, s[10:11]
	ds_read_b128 v[152:155], v200
	ds_read_b128 v[160:163], v200 offset:256
	v_ashrrev_i32_e32 v165, 31, v164
	v_or_b32_e32 v158, 48, v202
	v_lshl_add_u64 v[144:145], v[164:165], 4, s[10:11]
	v_ashrrev_i32_e32 v159, 31, v158
	v_lshl_add_u64 v[146:147], v[158:159], 4, s[10:11]
	ds_read_b128 v[176:179], v200 offset:512
	ds_read_b128 v[180:183], v200 offset:768
	v_add_u32_e32 v156, 0x80, v202
	v_ashrrev_i32_e32 v157, 31, v156
	v_add_u32_e32 v150, 0x90, v202
	v_lshl_add_u64 v[144:145], v[156:157], 4, s[10:11]
	v_ashrrev_i32_e32 v151, 31, v150
	v_lshl_add_u64 v[146:147], v[150:151], 4, s[10:11]
	ds_read_b128 v[184:187], v200 offset:2048
	ds_read_b128 v[188:191], v200 offset:2304
	v_add_u32_e32 v146, 0xa0, v202
	v_ashrrev_i32_e32 v147, 31, v146
	v_lshl_add_u64 v[144:145], v[146:147], 4, s[10:11]
	ds_read_b128 v[192:195], v200 offset:2560
	v_add_u32_e32 v144, 0xb0, v202
	v_ashrrev_i32_e32 v145, 31, v144
	v_lshl_add_u64 v[148:149], v[144:145], 4, s[10:11]
	ds_read_b128 v[196:199], v200 offset:2816
	s_branch .Lrsl6_join

;     __device__ __forceinline__ void operator()(const f32x4 (&acc)[2][2][4][2], const Unit& u, int wr, int wc, int fr, int fq) const {
;         float rsv[8];
; #pragma unroll
;         for (int idx = 0; idx < 8; ++idx) { const f32x4 q = *(const f32x4*)(rowss + (size_t)(u.pm * BM + (idx >> 2) * HALF + wr * 64 + (idx & 3) * 16 + fr) * 4); rsv[idx] = (q[0] + q[1]) + (q[2] + q[3]); }
; #pragma unroll
;         for (int ai = 0; ai < 2; ++ai)
; #pragma unroll
;             for (int m = 0; m < 4; ++m) {
;                 const int r = u.pm * BM + ai * HALF + wr * 64 + m * 16 + fr;
;                 const float rs = rsqrtf(rsv[ai * 4 + m] * (1.0f / DM) + EPS);
; #pragma unroll
;                 for (int bj = 0; bj < 2; ++bj) {
;                     f32x4 a = acc[ai][bj][m][0] * rs, b = acc[ai][bj][m][1] * rs;
; #pragma unroll
;                     for (int t = 0; t < 4; ++t) { a[t] = fmaxf(a[t], 0.f); a[t] *= a[t]; b[t] = fmaxf(b[t], 0.f); b[t] *= b[t]; }
;                     st8bf(U + (size_t)r * FF + u.pn * BM + wc * 64 + bj * 32 + 8 * fq, a, b);
;                 }
.Lrsl6_join:
	v_mov_b64_e32 v[148:149], s[22:23]
	s_lshl_b32 s34, s34, 8
	s_ashr_i32 s35, s34, 31
	v_lshlrev_b64 v[202:203], 13, v[202:203]
	s_lshl_b64 s[34:35], s[34:35], 1
	v_lshl_add_u64 v[202:203], s[4:5], 0, v[202:203]
	v_lshl_add_u64 v[202:203], v[202:203], 0, s[34:35]
	v_lshl_add_u64 v[202:203], v[202:203], 0, s[12:13]
	v_lshl_add_u64 v[202:203], v[202:203], 0, v[136:137]
	s_waitcnt vmcnt(0)
	s_waitcnt lgkmcnt(0)
	v_mov_b32_e32 v204, v153
	v_mov_b32_e32 v205, v154
	v_mov_b32_e32 v153, v155
	v_mov_b32_e32 v154, v161
	v_mov_b32_e32 v155, v162
	v_mov_b32_e32 v161, v163
	v_pk_add_f32 v[152:153], v[204:205], v[152:153]
	v_mov_b32_e32 v162, v177
	v_mov_b32_e32 v163, v178
	v_mov_b32_e32 v177, v179
	v_pk_add_f32 v[154:155], v[154:155], v[160:161]
	v_pk_add_f32 v[176:177], v[162:163], v[176:177]
	v_mov_b32_e32 v163, v152
	v_mov_b32_e32 v162, v154
	v_mov_b32_e32 v152, v155
	v_mov_b32_e32 v178, v181
	v_mov_b32_e32 v179, v182
	v_mov_b32_e32 v181, v183
	v_pk_add_f32 v[152:153], v[162:163], v[152:153]
	v_pk_add_f32 v[178:179], v[178:179], v[180:181]
	v_pk_fma_f32 v[180:181], v[152:153], s[20:21], v[148:149] op_sel_hi:[1,0,0]
	v_mov_b32_e32 v182, v185
	v_mul_f32_e32 v152, 0x4b800000, v181
	v_cmp_gt_f32_e32 vcc, s56, v181
	v_mov_b32_e32 v183, v186
	v_mov_b32_e32 v185, v187
	v_cndmask_b32_e32 v152, v181, v152, vcc
	v_rsq_f32_e32 v173, v152
	v_pk_add_f32 v[160:161], v[182:183], v[184:185]
	v_mov_b32_e32 v186, v189
	v_mov_b32_e32 v187, v190
	v_mul_f32_e32 v174, 0x45800000, v173
	v_cndmask_b32_e32 v174, v173, v174, vcc
	v_pk_mul_f32 v[126:127], v[126:127], v[174:175] op_sel_hi:[1,0]
	v_pk_mul_f32 v[124:125], v[124:125], v[174:175] op_sel_hi:[1,0]
	v_pk_mul_f32 v[122:123], v[122:123], v[174:175] op_sel_hi:[1,0]
	v_pk_mul_f32 v[120:121], v[120:121], v[174:175] op_sel_hi:[1,0]
	v_max_f32_e32 v124, 0, v124
	v_max_f32_e32 v120, 0, v120
	v_max_f32_e32 v125, 0, v125
	v_max_f32_e32 v121, 0, v121
	v_max_f32_e32 v126, 0, v126
	v_max_f32_e32 v122, 0, v122
	v_max_f32_e32 v127, 0, v127
	v_max_f32_e32 v123, 0, v123
	v_pk_mul_f32 v[124:125], v[124:125], v[124:125]
	v_pk_mul_f32 v[182:183], v[120:121], v[120:121]
	v_pk_mul_f32 v[126:127], v[126:127], v[126:127]
	v_pk_mul_f32 v[184:185], v[122:123], v[122:123]
	v_pk_mul_f32 v[114:115], v[114:115], v[174:175] op_sel_hi:[1,0]
	v_cvt_pk_bf16_f32 v120, v124, v125
	v_cvt_pk_bf16_f32 v121, v126, v127
	v_cvt_pk_bf16_f32 v122, v182, v183
	v_cvt_pk_bf16_f32 v123, v184, v185
	v_pk_mul_f32 v[116:117], v[116:117], v[174:175] op_sel_hi:[1,0]
	v_pk_mul_f32 v[112:113], v[112:113], v[174:175] op_sel_hi:[1,0]
	v_max_f32_e32 v114, 0, v114
	v_max_f32_e32 v115, 0, v115
	global_store_dwordx4 v[202:203], v[120:123], off
	v_pk_mul_f32 v[118:119], v[118:119], v[174:175] op_sel_hi:[1,0]
	v_max_f32_e32 v116, 0, v116
	v_max_f32_e32 v112, 0, v112
	v_max_f32_e32 v117, 0, v117
	v_max_f32_e32 v113, 0, v113
	v_pk_mul_f32 v[122:123], v[114:115], v[114:115]
	v_mul_f32_e32 v114, 0x4b800000, v180
	v_cmp_gt_f32_e32 vcc, s56, v180
	v_pk_mul_f32 v[116:117], v[116:117], v[116:117]
	v_pk_mul_f32 v[120:121], v[112:113], v[112:113]
	v_max_f32_e32 v112, 0, v118
	v_max_f32_e32 v113, 0, v119
	v_cndmask_b32_e32 v114, v180, v114, vcc
	v_pk_mul_f32 v[118:119], v[112:113], v[112:113]
	v_cvt_pk_bf16_f32 v112, v116, v117
	v_rsq_f32_e32 v116, v114
	v_cvt_pk_bf16_f32 v113, v118, v119
	v_cvt_pk_bf16_f32 v114, v120, v121
	v_cvt_pk_bf16_f32 v115, v122, v123
	global_store_dwordx4 v[202:203], v[112:115], off offset:64
	v_mov_b32_e32 v189, v191
	v_pk_add_f32 v[162:163], v[186:187], v[188:189]
	v_mul_f32_e32 v112, 0x45800000, v116
	v_cndmask_b32_e32 v112, v116, v112, vcc
	v_pk_mul_f32 v[104:105], v[104:105], v[112:113] op_sel_hi:[1,0]
	v_pk_mul_f32 v[110:111], v[110:111], v[112:113] op_sel_hi:[1,0]
	v_max_f32_e32 v104, 0, v104
	v_max_f32_e32 v105, 0, v105
	v_lshlrev_b64 v[114:115], 13, v[166:167]
	v_pk_mul_f32 v[116:117], v[104:105], v[104:105]
	v_max_f32_e32 v104, 0, v110
	v_max_f32_e32 v105, 0, v111
	v_pk_mul_f32 v[108:109], v[108:109], v[112:113] op_sel_hi:[1,0]
	v_pk_mul_f32 v[106:107], v[106:107], v[112:113] op_sel_hi:[1,0]
	v_pk_mul_f32 v[110:111], v[104:105], v[104:105]
	v_lshl_add_u64 v[104:105], s[4:5], 0, v[114:115]
	v_max_f32_e32 v108, 0, v108
	v_max_f32_e32 v109, 0, v109
	v_max_f32_e32 v106, 0, v106
	v_max_f32_e32 v107, 0, v107
	v_lshl_add_u64 v[104:105], v[104:105], 0, s[34:35]
	v_pk_mul_f32 v[108:109], v[108:109], v[108:109]
	v_pk_mul_f32 v[118:119], v[106:107], v[106:107]
	v_lshl_add_u64 v[104:105], v[104:105], 0, s[12:13]
	v_pk_mul_f32 v[96:97], v[96:97], v[112:113] op_sel_hi:[1,0]
	v_lshl_add_u64 v[114:115], v[104:105], 0, v[136:137]
	v_cvt_pk_bf16_f32 v104, v108, v109
	v_cvt_pk_bf16_f32 v105, v110, v111
	v_cvt_pk_bf16_f32 v106, v116, v117
	v_cvt_pk_bf16_f32 v107, v118, v119
	v_pk_mul_f32 v[102:103], v[102:103], v[112:113] op_sel_hi:[1,0]
	v_pk_mul_f32 v[100:101], v[100:101], v[112:113] op_sel_hi:[1,0]
	v_pk_mul_f32 v[98:99], v[98:99], v[112:113] op_sel_hi:[1,0]
	v_max_f32_e32 v96, 0, v96
	v_max_f32_e32 v97, 0, v97
	global_store_dwordx4 v[114:115], v[104:107], off
	v_max_f32_e32 v100, 0, v100
	v_max_f32_e32 v101, 0, v101
	v_pk_mul_f32 v[104:105], v[96:97], v[96:97]
	v_max_f32_e32 v96, 0, v102
	v_max_f32_e32 v98, 0, v98
	v_max_f32_e32 v97, 0, v103
	v_max_f32_e32 v99, 0, v99
	v_pk_mul_f32 v[100:101], v[100:101], v[100:101]
	v_pk_mul_f32 v[102:103], v[96:97], v[96:97]
	v_pk_mul_f32 v[106:107], v[98:99], v[98:99]
	v_cvt_pk_bf16_f32 v96, v100, v101
	v_cvt_pk_bf16_f32 v97, v102, v103
	v_cvt_pk_bf16_f32 v98, v104, v105
	v_cvt_pk_bf16_f32 v99, v106, v107
	global_store_dwordx4 v[114:115], v[96:99], off offset:64
	v_mov_b32_e32 v190, v193
	v_mov_b32_e32 v191, v194
;     __device__ __forceinline__ void operator()(const f32x4 (&acc)[2][2][4][2], const Unit& u, int wr, int wc, int fr, int fq) const {
;     ...
; #pragma unroll
;         for (int ai = 0; ai < 2; ++ai)
; #pragma unroll
;             for (int m = 0; m < 4; ++m) {
;                 const int r = u.pm * BM + ai * HALF + wr * 64 + m * 16 + fr;
;                 const float rs = rsqrtf(rsv[ai * 4 + m] * (1.0f / DM) + EPS);
; #pragma unroll
;                 for (int bj = 0; bj < 2; ++bj) {
;                     f32x4 a = acc[ai][bj][m][0] * rs, b = acc[ai][bj][m][1] * rs;
; #pragma unroll
;                     for (int t = 0; t < 4; ++t) { a[t] = fmaxf(a[t], 0.f); a[t] *= a[t]; b[t] = fmaxf(b[t], 0.f); b[t] *= b[t]; }
;                     st8bf(U + (size_t)r * FF + u.pn * BM + wc * 64 + bj * 32 + 8 * fq, a, b);
;                 }
	v_mov_b32_e32 v98, v178
	v_mov_b32_e32 v99, v176
	v_mov_b32_e32 v176, v179
	v_pk_add_f32 v[98:99], v[98:99], v[176:177]
	v_lshlrev_b64 v[96:97], 13, v[164:165]
	v_pk_fma_f32 v[98:99], v[98:99], s[20:21], v[148:149] op_sel_hi:[1,0,0]
	v_lshl_add_u64 v[96:97], s[4:5], 0, v[96:97]
	v_mul_f32_e32 v100, 0x4b800000, v99
	v_cmp_gt_f32_e32 vcc, s56, v99
	v_lshl_add_u64 v[96:97], v[96:97], 0, s[34:35]
	v_lshl_add_u64 v[96:97], v[96:97], 0, s[12:13]
	v_cndmask_b32_e32 v99, v99, v100, vcc
	v_rsq_f32_e32 v99, v99
	v_lshl_add_u64 v[96:97], v[96:97], 0, v[136:137]
	v_mov_b32_e32 v193, v195
	v_mov_b32_e32 v194, v197
	v_mul_f32_e32 v100, 0x45800000, v99
	v_cndmask_b32_e32 v100, v99, v100, vcc
	v_pk_mul_f32 v[88:89], v[88:89], v[100:101] op_sel_hi:[1,0]
	v_pk_mul_f32 v[94:95], v[94:95], v[100:101] op_sel_hi:[1,0]
	v_pk_mul_f32 v[92:93], v[92:93], v[100:101] op_sel_hi:[1,0]
	v_pk_mul_f32 v[90:91], v[90:91], v[100:101] op_sel_hi:[1,0]
	v_max_f32_e32 v88, 0, v88
	v_max_f32_e32 v89, 0, v89
	v_max_f32_e32 v92, 0, v92
	v_max_f32_e32 v93, 0, v93
	v_pk_mul_f32 v[102:103], v[88:89], v[88:89]
	v_max_f32_e32 v88, 0, v94
	v_max_f32_e32 v90, 0, v90
	v_max_f32_e32 v89, 0, v95
	v_max_f32_e32 v91, 0, v91
	v_pk_mul_f32 v[92:93], v[92:93], v[92:93]
	v_pk_mul_f32 v[94:95], v[88:89], v[88:89]
	v_pk_mul_f32 v[104:105], v[90:91], v[90:91]
	v_pk_mul_f32 v[82:83], v[82:83], v[100:101] op_sel_hi:[1,0]
	v_cvt_pk_bf16_f32 v88, v92, v93
	v_cvt_pk_bf16_f32 v89, v94, v95
	v_cvt_pk_bf16_f32 v90, v102, v103
	v_cvt_pk_bf16_f32 v91, v104, v105
	v_pk_mul_f32 v[84:85], v[84:85], v[100:101] op_sel_hi:[1,0]
	v_pk_mul_f32 v[80:81], v[80:81], v[100:101] op_sel_hi:[1,0]
	v_max_f32_e32 v82, 0, v82
	v_max_f32_e32 v83, 0, v83
	global_store_dwordx4 v[96:97], v[88:91], off
	v_pk_mul_f32 v[86:87], v[86:87], v[100:101] op_sel_hi:[1,0]
	v_max_f32_e32 v84, 0, v84
	v_max_f32_e32 v80, 0, v80
	v_max_f32_e32 v85, 0, v85
	v_max_f32_e32 v81, 0, v81
	v_pk_mul_f32 v[90:91], v[82:83], v[82:83]
	v_mul_f32_e32 v82, 0x4b800000, v98
	v_cmp_gt_f32_e32 vcc, s56, v98
	v_pk_mul_f32 v[84:85], v[84:85], v[84:85]
	v_pk_mul_f32 v[88:89], v[80:81], v[80:81]
	v_max_f32_e32 v80, 0, v86
	v_max_f32_e32 v81, 0, v87
	v_cndmask_b32_e32 v82, v98, v82, vcc
	v_pk_mul_f32 v[86:87], v[80:81], v[80:81]
	v_cvt_pk_bf16_f32 v80, v84, v85
	v_rsq_f32_e32 v84, v82
	v_cvt_pk_bf16_f32 v81, v86, v87
	v_cvt_pk_bf16_f32 v82, v88, v89
	v_cvt_pk_bf16_f32 v83, v90, v91
	global_store_dwordx4 v[96:97], v[80:83], off offset:64
	v_mov_b32_e32 v195, v198
	v_mov_b32_e32 v197, v199
	v_mul_f32_e32 v80, 0x45800000, v84
	v_cndmask_b32_e32 v80, v84, v80, vcc
	v_pk_mul_f32 v[72:73], v[72:73], v[80:81] op_sel_hi:[1,0]
	v_pk_mul_f32 v[78:79], v[78:79], v[80:81] op_sel_hi:[1,0]
	v_max_f32_e32 v72, 0, v72
	v_max_f32_e32 v73, 0, v73
	v_lshlrev_b64 v[82:83], 13, v[158:159]
	v_pk_mul_f32 v[84:85], v[72:73], v[72:73]
	v_max_f32_e32 v72, 0, v78
	v_max_f32_e32 v73, 0, v79
	v_pk_mul_f32 v[76:77], v[76:77], v[80:81] op_sel_hi:[1,0]
	v_pk_mul_f32 v[74:75], v[74:75], v[80:81] op_sel_hi:[1,0]
	v_pk_mul_f32 v[78:79], v[72:73], v[72:73]
	v_lshl_add_u64 v[72:73], s[4:5], 0, v[82:83]
	v_max_f32_e32 v76, 0, v76
	v_max_f32_e32 v77, 0, v77
	v_max_f32_e32 v74, 0, v74
	v_max_f32_e32 v75, 0, v75
	v_lshl_add_u64 v[72:73], v[72:73], 0, s[34:35]
	v_pk_mul_f32 v[76:77], v[76:77], v[76:77]
	v_pk_mul_f32 v[86:87], v[74:75], v[74:75]
	v_lshl_add_u64 v[72:73], v[72:73], 0, s[12:13]
	v_pk_mul_f32 v[64:65], v[64:65], v[80:81] op_sel_hi:[1,0]
	v_lshl_add_u64 v[82:83], v[72:73], 0, v[136:137]
	v_cvt_pk_bf16_f32 v72, v76, v77
	v_cvt_pk_bf16_f32 v73, v78, v79
	v_cvt_pk_bf16_f32 v74, v84, v85
	v_cvt_pk_bf16_f32 v75, v86, v87
	v_pk_mul_f32 v[70:71], v[70:71], v[80:81] op_sel_hi:[1,0]
	v_pk_mul_f32 v[68:69], v[68:69], v[80:81] op_sel_hi:[1,0]
	v_pk_mul_f32 v[66:67], v[66:67], v[80:81] op_sel_hi:[1,0]
	v_max_f32_e32 v64, 0, v64
	v_max_f32_e32 v65, 0, v65
	global_store_dwordx4 v[82:83], v[72:75], off
	v_max_f32_e32 v68, 0, v68
	v_max_f32_e32 v69, 0, v69
	v_pk_mul_f32 v[72:73], v[64:65], v[64:65]
	v_max_f32_e32 v64, 0, v70
	v_max_f32_e32 v66, 0, v66
	v_max_f32_e32 v65, 0, v71
	v_max_f32_e32 v67, 0, v67
	v_pk_mul_f32 v[68:69], v[68:69], v[68:69]
	v_pk_mul_f32 v[70:71], v[64:65], v[64:65]
	v_pk_mul_f32 v[74:75], v[66:67], v[66:67]
	v_cvt_pk_bf16_f32 v64, v68, v69
	v_cvt_pk_bf16_f32 v65, v70, v71
	v_cvt_pk_bf16_f32 v66, v72, v73
	v_cvt_pk_bf16_f32 v67, v74, v75
	global_store_dwordx4 v[82:83], v[64:67], off offset:64
	v_pk_add_f32 v[152:153], v[190:191], v[192:193]
	v_pk_add_f32 v[154:155], v[194:195], v[196:197]
	v_mov_b32_e32 v66, v162
	v_mov_b32_e32 v67, v160
	v_mov_b32_e32 v160, v163
	v_pk_add_f32 v[66:67], v[66:67], v[160:161]
	v_lshlrev_b64 v[64:65], 13, v[156:157]
	v_pk_fma_f32 v[66:67], v[66:67], s[20:21], v[148:149] op_sel_hi:[1,0,0]
	v_lshl_add_u64 v[64:65], s[4:5], 0, v[64:65]
	v_mul_f32_e32 v68, 0x4b800000, v67
	v_cmp_gt_f32_e32 vcc, s56, v67
	v_lshl_add_u64 v[64:65], v[64:65], 0, s[34:35]
	v_lshl_add_u64 v[64:65], v[64:65], 0, s[12:13]
	v_cndmask_b32_e32 v67, v67, v68, vcc
	v_rsq_f32_e32 v67, v67
	v_lshl_add_u64 v[64:65], v[64:65], 0, v[136:137]
	v_mul_f32_e32 v68, 0x45800000, v67
	v_cndmask_b32_e32 v68, v67, v68, vcc
	v_pk_mul_f32 v[56:57], v[56:57], v[68:69] op_sel_hi:[1,0]
	v_pk_mul_f32 v[62:63], v[62:63], v[68:69] op_sel_hi:[1,0]
	v_pk_mul_f32 v[60:61], v[60:61], v[68:69] op_sel_hi:[1,0]
	v_pk_mul_f32 v[58:59], v[58:59], v[68:69] op_sel_hi:[1,0]
	v_max_f32_e32 v56, 0, v56
	v_max_f32_e32 v57, 0, v57
	v_max_f32_e32 v60, 0, v60
	v_max_f32_e32 v61, 0, v61
	v_pk_mul_f32 v[70:71], v[56:57], v[56:57]
	v_max_f32_e32 v56, 0, v62
	v_max_f32_e32 v58, 0, v58
	v_max_f32_e32 v57, 0, v63
	v_max_f32_e32 v59, 0, v59
;     __device__ __forceinline__ void operator()(const f32x4 (&acc)[2][2][4][2], const Unit& u, int wr, int wc, int fr, int fq) const {
;     ...
; #pragma unroll
;         for (int ai = 0; ai < 2; ++ai)
; #pragma unroll
;             for (int m = 0; m < 4; ++m) {
;                 const int r = u.pm * BM + ai * HALF + wr * 64 + m * 16 + fr;
;                 const float rs = rsqrtf(rsv[ai * 4 + m] * (1.0f / DM) + EPS);
; #pragma unroll
;                 for (int bj = 0; bj < 2; ++bj) {
;                     f32x4 a = acc[ai][bj][m][0] * rs, b = acc[ai][bj][m][1] * rs;
; #pragma unroll
;                     for (int t = 0; t < 4; ++t) { a[t] = fmaxf(a[t], 0.f); a[t] *= a[t]; b[t] = fmaxf(b[t], 0.f); b[t] *= b[t]; }
;                     st8bf(U + (size_t)r * FF + u.pn * BM + wc * 64 + bj * 32 + 8 * fq, a, b);
;                 }
	v_pk_mul_f32 v[60:61], v[60:61], v[60:61]
	v_pk_mul_f32 v[62:63], v[56:57], v[56:57]
	v_pk_mul_f32 v[72:73], v[58:59], v[58:59]
	v_pk_mul_f32 v[50:51], v[50:51], v[68:69] op_sel_hi:[1,0]
	v_cvt_pk_bf16_f32 v56, v60, v61
	v_cvt_pk_bf16_f32 v57, v62, v63
	v_cvt_pk_bf16_f32 v58, v70, v71
	v_cvt_pk_bf16_f32 v59, v72, v73
	v_pk_mul_f32 v[52:53], v[52:53], v[68:69] op_sel_hi:[1,0]
	v_pk_mul_f32 v[48:49], v[48:49], v[68:69] op_sel_hi:[1,0]
	v_max_f32_e32 v50, 0, v50
	v_max_f32_e32 v51, 0, v51
	global_store_dwordx4 v[64:65], v[56:59], off
	v_pk_mul_f32 v[54:55], v[54:55], v[68:69] op_sel_hi:[1,0]
	v_max_f32_e32 v52, 0, v52
	v_max_f32_e32 v48, 0, v48
	v_max_f32_e32 v53, 0, v53
	v_max_f32_e32 v49, 0, v49
	v_pk_mul_f32 v[58:59], v[50:51], v[50:51]
	v_mul_f32_e32 v50, 0x4b800000, v66
	v_cmp_gt_f32_e32 vcc, s56, v66
	v_pk_mul_f32 v[52:53], v[52:53], v[52:53]
	v_pk_mul_f32 v[56:57], v[48:49], v[48:49]
	v_max_f32_e32 v48, 0, v54
	v_max_f32_e32 v49, 0, v55
	v_cndmask_b32_e32 v50, v66, v50, vcc
	v_pk_mul_f32 v[54:55], v[48:49], v[48:49]
	v_cvt_pk_bf16_f32 v48, v52, v53
	v_rsq_f32_e32 v52, v50
	v_cvt_pk_bf16_f32 v49, v54, v55
	v_cvt_pk_bf16_f32 v50, v56, v57
	v_cvt_pk_bf16_f32 v51, v58, v59
	global_store_dwordx4 v[64:65], v[48:51], off offset:64
	s_nop 1
	v_mul_f32_e32 v48, 0x45800000, v52
	v_cndmask_b32_e32 v48, v52, v48, vcc
	v_pk_mul_f32 v[40:41], v[40:41], v[48:49] op_sel_hi:[1,0]
	v_pk_mul_f32 v[46:47], v[46:47], v[48:49] op_sel_hi:[1,0]
	v_max_f32_e32 v40, 0, v40
	v_max_f32_e32 v41, 0, v41
	v_lshlrev_b64 v[50:51], 13, v[150:151]
	v_pk_mul_f32 v[52:53], v[40:41], v[40:41]
	v_max_f32_e32 v40, 0, v46
	v_max_f32_e32 v41, 0, v47
	v_pk_mul_f32 v[44:45], v[44:45], v[48:49] op_sel_hi:[1,0]
	v_pk_mul_f32 v[42:43], v[42:43], v[48:49] op_sel_hi:[1,0]
	v_pk_mul_f32 v[46:47], v[40:41], v[40:41]
	v_lshl_add_u64 v[40:41], s[4:5], 0, v[50:51]
	v_max_f32_e32 v44, 0, v44
	v_max_f32_e32 v45, 0, v45
	v_max_f32_e32 v42, 0, v42
	v_max_f32_e32 v43, 0, v43
	v_lshl_add_u64 v[40:41], v[40:41], 0, s[34:35]
	v_pk_mul_f32 v[44:45], v[44:45], v[44:45]
	v_pk_mul_f32 v[54:55], v[42:43], v[42:43]
	v_lshl_add_u64 v[40:41], v[40:41], 0, s[12:13]
	v_pk_mul_f32 v[32:33], v[32:33], v[48:49] op_sel_hi:[1,0]
	v_lshl_add_u64 v[50:51], v[40:41], 0, v[136:137]
	v_cvt_pk_bf16_f32 v40, v44, v45
	v_cvt_pk_bf16_f32 v41, v46, v47
	v_cvt_pk_bf16_f32 v42, v52, v53
	v_cvt_pk_bf16_f32 v43, v54, v55
	v_pk_mul_f32 v[38:39], v[38:39], v[48:49] op_sel_hi:[1,0]
	v_pk_mul_f32 v[36:37], v[36:37], v[48:49] op_sel_hi:[1,0]
	v_pk_mul_f32 v[34:35], v[34:35], v[48:49] op_sel_hi:[1,0]
	v_max_f32_e32 v32, 0, v32
	v_max_f32_e32 v33, 0, v33
	global_store_dwordx4 v[50:51], v[40:43], off
	v_max_f32_e32 v36, 0, v36
	v_max_f32_e32 v37, 0, v37
	v_pk_mul_f32 v[40:41], v[32:33], v[32:33]
	v_max_f32_e32 v32, 0, v38
	v_max_f32_e32 v34, 0, v34
	v_max_f32_e32 v33, 0, v39
	v_max_f32_e32 v35, 0, v35
	v_pk_mul_f32 v[36:37], v[36:37], v[36:37]
	v_pk_mul_f32 v[38:39], v[32:33], v[32:33]
	v_pk_mul_f32 v[42:43], v[34:35], v[34:35]
	v_cvt_pk_bf16_f32 v32, v36, v37
	v_cvt_pk_bf16_f32 v33, v38, v39
	v_cvt_pk_bf16_f32 v34, v40, v41
	v_cvt_pk_bf16_f32 v35, v42, v43
	global_store_dwordx4 v[50:51], v[32:35], off offset:64
	s_nop 1
	v_mov_b32_e32 v34, v154
	v_mov_b32_e32 v35, v152
	v_mov_b32_e32 v152, v155
	v_pk_add_f32 v[34:35], v[34:35], v[152:153]
	v_lshlrev_b64 v[32:33], 13, v[146:147]
	v_pk_fma_f32 v[34:35], v[34:35], s[20:21], v[148:149] op_sel_hi:[1,0,0]
	v_lshl_add_u64 v[32:33], s[4:5], 0, v[32:33]
	v_mul_f32_e32 v36, 0x4b800000, v35
	v_cmp_gt_f32_e32 vcc, s56, v35
	v_lshl_add_u64 v[32:33], v[32:33], 0, s[34:35]
	v_lshl_add_u64 v[32:33], v[32:33], 0, s[12:13]
	v_cndmask_b32_e32 v35, v35, v36, vcc
	v_rsq_f32_e32 v35, v35
	v_lshl_add_u64 v[32:33], v[32:33], 0, v[136:137]
	v_mul_f32_e32 v36, 0x45800000, v35
;     __device__ __forceinline__ void operator()(const f32x4 (&acc)[2][2][4][2], const Unit& u, int wr, int wc, int fr, int fq) const {
;     ...
; #pragma unroll
;         for (int ai = 0; ai < 2; ++ai)
; #pragma unroll
;             for (int m = 0; m < 4; ++m) {
;                 const int r = u.pm * BM + ai * HALF + wr * 64 + m * 16 + fr;
;                 const float rs = rsqrtf(rsv[ai * 4 + m] * (1.0f / DM) + EPS);
; #pragma unroll
;                 for (int bj = 0; bj < 2; ++bj) {
;                     f32x4 a = acc[ai][bj][m][0] * rs, b = acc[ai][bj][m][1] * rs;
; #pragma unroll
;                     for (int t = 0; t < 4; ++t) { a[t] = fmaxf(a[t], 0.f); a[t] *= a[t]; b[t] = fmaxf(b[t], 0.f); b[t] *= b[t]; }
;                     st8bf(U + (size_t)r * FF + u.pn * BM + wc * 64 + bj * 32 + 8 * fq, a, b);
;                 }
	v_cndmask_b32_e32 v36, v35, v36, vcc
	v_pk_mul_f32 v[24:25], v[24:25], v[36:37] op_sel_hi:[1,0]
	v_pk_mul_f32 v[30:31], v[30:31], v[36:37] op_sel_hi:[1,0]
	v_pk_mul_f32 v[28:29], v[28:29], v[36:37] op_sel_hi:[1,0]
	v_pk_mul_f32 v[26:27], v[26:27], v[36:37] op_sel_hi:[1,0]
	v_max_f32_e32 v24, 0, v24
	v_max_f32_e32 v25, 0, v25
	v_max_f32_e32 v28, 0, v28
	v_max_f32_e32 v29, 0, v29
	v_pk_mul_f32 v[38:39], v[24:25], v[24:25]
	v_max_f32_e32 v24, 0, v30
	v_max_f32_e32 v26, 0, v26
	v_max_f32_e32 v25, 0, v31
	v_max_f32_e32 v27, 0, v27
	v_pk_mul_f32 v[28:29], v[28:29], v[28:29]
	v_pk_mul_f32 v[30:31], v[24:25], v[24:25]
	v_pk_mul_f32 v[40:41], v[26:27], v[26:27]
	v_pk_mul_f32 v[18:19], v[18:19], v[36:37] op_sel_hi:[1,0]
	v_cvt_pk_bf16_f32 v24, v28, v29
	v_cvt_pk_bf16_f32 v25, v30, v31
	v_cvt_pk_bf16_f32 v26, v38, v39
	v_cvt_pk_bf16_f32 v27, v40, v41
	v_pk_mul_f32 v[20:21], v[20:21], v[36:37] op_sel_hi:[1,0]
	v_pk_mul_f32 v[16:17], v[16:17], v[36:37] op_sel_hi:[1,0]
	v_max_f32_e32 v18, 0, v18
	v_max_f32_e32 v19, 0, v19
	global_store_dwordx4 v[32:33], v[24:27], off
	v_pk_mul_f32 v[22:23], v[22:23], v[36:37] op_sel_hi:[1,0]
	v_max_f32_e32 v20, 0, v20
	v_max_f32_e32 v16, 0, v16
	v_max_f32_e32 v21, 0, v21
	v_max_f32_e32 v17, 0, v17
	v_pk_mul_f32 v[26:27], v[18:19], v[18:19]
	v_mul_f32_e32 v18, 0x4b800000, v34
	v_cmp_gt_f32_e32 vcc, s56, v34
	v_pk_mul_f32 v[20:21], v[20:21], v[20:21]
	v_pk_mul_f32 v[24:25], v[16:17], v[16:17]
	v_max_f32_e32 v16, 0, v22
	v_max_f32_e32 v17, 0, v23
	v_cndmask_b32_e32 v18, v34, v18, vcc
	v_pk_mul_f32 v[22:23], v[16:17], v[16:17]
	v_cvt_pk_bf16_f32 v16, v20, v21
	v_rsq_f32_e32 v20, v18
	v_cvt_pk_bf16_f32 v17, v22, v23
	v_cvt_pk_bf16_f32 v18, v24, v25
	v_cvt_pk_bf16_f32 v19, v26, v27
	global_store_dwordx4 v[32:33], v[16:19], off offset:64
	s_nop 1
	v_mul_f32_e32 v16, 0x45800000, v20
	v_cndmask_b32_e32 v16, v20, v16, vcc
	v_pk_mul_f32 v[8:9], v[8:9], v[16:17] op_sel_hi:[1,0]
	v_pk_mul_f32 v[14:15], v[14:15], v[16:17] op_sel_hi:[1,0]
	v_max_f32_e32 v8, 0, v8
	v_max_f32_e32 v9, 0, v9
	v_lshlrev_b64 v[18:19], 13, v[144:145]
	v_pk_mul_f32 v[20:21], v[8:9], v[8:9]
	v_max_f32_e32 v8, 0, v14
	v_max_f32_e32 v9, 0, v15
	v_pk_mul_f32 v[12:13], v[12:13], v[16:17] op_sel_hi:[1,0]
	v_pk_mul_f32 v[10:11], v[10:11], v[16:17] op_sel_hi:[1,0]
	v_pk_mul_f32 v[14:15], v[8:9], v[8:9]
	v_lshl_add_u64 v[8:9], s[4:5], 0, v[18:19]
	v_max_f32_e32 v12, 0, v12
	v_max_f32_e32 v13, 0, v13
	v_max_f32_e32 v10, 0, v10
	v_max_f32_e32 v11, 0, v11
	v_lshl_add_u64 v[8:9], v[8:9], 0, s[34:35]
	v_pk_mul_f32 v[12:13], v[12:13], v[12:13]
	v_pk_mul_f32 v[22:23], v[10:11], v[10:11]
	v_lshl_add_u64 v[8:9], v[8:9], 0, s[12:13]
	v_pk_mul_f32 v[0:1], v[0:1], v[16:17] op_sel_hi:[1,0]
	v_lshl_add_u64 v[18:19], v[8:9], 0, v[136:137]
	v_cvt_pk_bf16_f32 v8, v12, v13
	v_cvt_pk_bf16_f32 v9, v14, v15
	v_cvt_pk_bf16_f32 v10, v20, v21
	v_cvt_pk_bf16_f32 v11, v22, v23
	v_pk_mul_f32 v[6:7], v[6:7], v[16:17] op_sel_hi:[1,0]
	v_pk_mul_f32 v[4:5], v[4:5], v[16:17] op_sel_hi:[1,0]
	v_pk_mul_f32 v[2:3], v[2:3], v[16:17] op_sel_hi:[1,0]
	v_max_f32_e32 v0, 0, v0
	v_max_f32_e32 v1, 0, v1
	global_store_dwordx4 v[18:19], v[8:11], off
	v_max_f32_e32 v4, 0, v4
	v_max_f32_e32 v5, 0, v5
	v_pk_mul_f32 v[8:9], v[0:1], v[0:1]
	v_max_f32_e32 v0, 0, v6
	v_max_f32_e32 v2, 0, v2
	v_max_f32_e32 v1, 0, v7
	v_max_f32_e32 v3, 0, v3
	v_pk_mul_f32 v[4:5], v[4:5], v[4:5]
	v_pk_mul_f32 v[6:7], v[0:1], v[0:1]
	v_pk_mul_f32 v[10:11], v[2:3], v[2:3]
	v_cvt_pk_bf16_f32 v0, v4, v5
	v_cvt_pk_bf16_f32 v1, v6, v7
	v_cvt_pk_bf16_f32 v2, v8, v9
	v_cvt_pk_bf16_f32 v3, v10, v11
	s_andn2_b64 vcc, exec, s[0:1]
	s_mov_b64 s[0:1], -1
	global_store_dwordx4 v[18:19], v[0:3], off offset:64
	s_cbranch_vccnz .LBB0_973
	s_andn2_b64 vcc, exec, s[14:15]
	s_cbranch_vccnz .LBB0_972
	s_barrier
	s_branch .LBB0_972
